# waves 4-7 issue their K/V tile DMAs before the first LDS fragment reads (small stagger vs waves 0-3)
# baseline (speedup 1.0000x reference)
; template <bool NOMAX>
; __device__ __forceinline__ void attn_block(const Params& P, LAS unsigned char* lds, int qR0, int h, int kR0, int kR1, int ntiles, int jmax, int nlast, int qvalid) {
;     ...
;         if (j + 1 < ntiles) { const int Rn = (kR1 >= 0 && j + 1 >= 16) ? kR1 : kR0 + 64 * (j + 1);
;             attn_stage_issue(P, lds, st, Rn, buf ^ 1, tid); }
;         if (j <= jmax) {
;             const LAS unsigned char* kb = lds + L_K0 + buf * KBUF + r * 384; const LAS unsigned char* vb = lds + L_V0 + buf * VBUF + r * 128;
;             const LAS unsigned char* rkb = lds + L_RKT + j * 256 + 16 * hh;
;             f32x16 sacc[2];
; #pragma unroll
;             for (int kt = 0; kt < 2; ++kt) {
; #pragma unroll
;                 for (int e = 0; e < 16; ++e) sacc[kt][e] = 0.f;
; #pragma unroll
;                 for (int s = 0; s < 12; ++s) { const bf16x8 kf = *(const LAS bf16x8*)(kb + kt * (32 * 384) + (s >> 2) * 128 + oc[s & 3]); sacc[kt] = mfma32(kf, qf[s], sacc[kt]); }
;             }
; #pragma unroll
;             for (int kt = 0; kt < 2; ++kt)
; #pragma unroll
;                 for (int gq = 0; gq < 4; ++gq) { const f32x4 rk4 = *(const LAS f32x4*)(rkb + (32 * kt + 8 * gq) * 4);
; #pragma unroll
;                     for (int i = 0; i < 4; ++i) sacc[kt][4 * gq + i] *= rk4[i]; }
;             if (j == ntiles - 1 && nlast < 64) {
; #pragma unroll
;                 for (int kt = 0; kt < 2; ++kt)
; #pragma unroll
;                     for (int e = 0; e < 16; ++e) { const int key = 32 * kt + (e & 3) + 8 * (e >> 2) + 4 * hh; if (key >= nlast) sacc[kt][e] = -1e30f; } }
;             float mnew = 0.f;
;             if constexpr (!NOMAX) {
;                 float mx = sacc[0][0];
; #pragma unroll
;                 for (int kt = 0; kt < 2; ++kt)
; #pragma unroll
;                     for (int e = 0; e < 16; ++e) mx = fmaxf(mx, sacc[kt][e]);
;                 mx = fmaxf(mx, __shfl_xor(mx, 32));
;                 const float mcand = fmaxf(mrun, mx);
;                 if (__any(mcand > mrun + 8.0f)) { const float alpha = __builtin_amdgcn_exp2f(mrun - mcand); lrun *= alpha;
; #pragma unroll
;                     for (int dt = 0; dt < 4; ++dt)
; #pragma unroll
;                         for (int e = 0; e < 16; ++e) oacc[dt][e] *= alpha;
;                     mrun = mcand; }
;                 mnew = mrun;
;             }
;             float ps = 0.f;
; #pragma unroll
.LBB0_1019:
	s_and_b32 s57, s14, 1
	s_xor_b32 s12, s57, 1
	v_readfirstlane_b32 s13, v169
	s_ashr_i32 s13, s13, 6
	s_lshr_b32 s61, s13, 2
	s_mul_i32 s58, s12, 0x6000
	s_mul_i32 s59, s13, 0xc00
	s_add_i32 s59, s58, s59
	s_lshl_b32 s12, s12, 14
	s_lshl_b32 s13, s13, 11
	s_add_i32 s60, s12, s13
	s_add_i32 s60, s60, 0xc000
	v_cmp_le_i32_e32 vcc, s14, v163
	s_cbranch_vccz .Lattn_inact_a
	s_cmp_lg_u32 s61, 0
	s_cbranch_scc1 .Lattn_late_a
	s_mul_i32 s58, s57, 0x6000
	v_add_u32_e32 v253, s58, v177
	v_add_u32_e32 v214, v253, v168
	v_add_u32_e32 v215, v253, v167
	v_add_u32_e32 v216, v253, v166
	v_add_u32_e32 v217, v253, v165
	ds_read_b128 v[182:185], v214
	ds_read_b128 v[186:189], v215
	ds_read_b128 v[190:193], v216
	ds_read_b128 v[194:197], v217
	ds_read_b128 v[198:201], v214 offset:128
	ds_read_b128 v[202:205], v215 offset:128
	v_lshl_add_u32 v254, v181, v173, v170
	s_mov_b32 m0, s59
	s_nop 0
	global_load_lds_dwordx4 v254, s[18:19]
	v_lshl_add_u32 v254, v181, v174, v171
	s_add_i32 m0, s59, 0x400
	s_nop 0
	global_load_lds_dwordx4 v254, s[18:19]
	v_lshl_add_u32 v254, v181, v175, v172
	s_add_i32 m0, s59, 0x800
	s_nop 0
	global_load_lds_dwordx4 v254, s[18:19]
	s_waitcnt lgkmcnt(5)
	v_mfma_f32_32x32x16_bf16 v[64:79], v[182:185], v[100:103], 0
	ds_read_b128 v[206:209], v216 offset:128
	s_mov_b32 m0, s60
	s_nop 0
	global_load_lds_dwordx4 v180, s[18:19]
	v_add_u32_e32 v219, s56, v178
	s_waitcnt lgkmcnt(5)
	v_mfma_f32_32x32x16_bf16 v[64:79], v[186:189], v[104:107], v[64:79]
	ds_read_b128 v[210:213], v217 offset:128
	s_add_i32 m0, s60, 0x400
	s_nop 0
	global_load_lds_dwordx4 v179, s[18:19]
	v_add_u32_e32 v219, 0x14300, v219
	s_waitcnt lgkmcnt(5)
	v_mfma_f32_32x32x16_bf16 v[64:79], v[190:193], v[108:111], v[64:79]
	ds_read_b128 v[182:185], v214 offset:256
	v_lshl_add_u32 v218, s57, 14, v176
	s_waitcnt lgkmcnt(5)
	v_mfma_f32_32x32x16_bf16 v[64:79], v[194:197], v[112:115], v[64:79]
	ds_read_b128 v[186:189], v215 offset:256
	v_sub_u32_e32 v218, v218, v253
	s_waitcnt lgkmcnt(5)
	v_mfma_f32_32x32x16_bf16 v[64:79], v[198:201], v[116:119], v[64:79]
	ds_read_b128 v[190:193], v216 offset:256
	s_waitcnt lgkmcnt(5)
	v_mfma_f32_32x32x16_bf16 v[64:79], v[202:205], v[120:123], v[64:79]
	ds_read_b128 v[194:197], v217 offset:256
	s_waitcnt lgkmcnt(5)
	v_mfma_f32_32x32x16_bf16 v[64:79], v[206:209], v[124:127], v[64:79]
	ds_read_b128 v[198:201], v214 offset:12288
	s_waitcnt lgkmcnt(5)
	v_mfma_f32_32x32x16_bf16 v[64:79], v[210:213], v[128:131], v[64:79]
	ds_read_b128 v[202:205], v215 offset:12288
	s_waitcnt lgkmcnt(5)
	v_mfma_f32_32x32x16_bf16 v[64:79], v[182:185], v[132:135], v[64:79]
	ds_read_b128 v[206:209], v216 offset:12288
	s_waitcnt lgkmcnt(5)
	v_mfma_f32_32x32x16_bf16 v[64:79], v[186:189], v[136:139], v[64:79]
	ds_read_b128 v[210:213], v217 offset:12288
	ds_read_b128 v[232:235], v219
	s_waitcnt lgkmcnt(6)
	v_mfma_f32_32x32x16_bf16 v[64:79], v[190:193], v[140:143], v[64:79]
	ds_read_b128 v[182:185], v214 offset:12416
	ds_read_b128 v[236:239], v219 offset:32
	s_waitcnt lgkmcnt(7)
	v_mfma_f32_32x32x16_bf16 v[64:79], v[194:197], v[144:147], v[64:79]
	ds_read_b128 v[186:189], v215 offset:12416
	ds_read_b128 v[240:243], v219 offset:64
	s_waitcnt lgkmcnt(8)
	v_mfma_f32_32x32x16_bf16 v[80:95], v[198:201], v[100:103], 0
	ds_read_b128 v[190:193], v216 offset:12416
	ds_read_b128 v[244:247], v219 offset:96
	s_waitcnt lgkmcnt(9)
	v_mfma_f32_32x32x16_bf16 v[80:95], v[202:205], v[104:107], v[80:95]
	ds_read_b128 v[194:197], v217 offset:12416
	s_waitcnt lgkmcnt(9)
	v_mfma_f32_32x32x16_bf16 v[80:95], v[206:209], v[108:111], v[80:95]
	ds_read_b128 v[198:201], v214 offset:12544
	s_waitcnt lgkmcnt(9)
	v_mfma_f32_32x32x16_bf16 v[80:95], v[210:213], v[112:115], v[80:95]
	ds_read_b128 v[202:205], v215 offset:12544
	s_waitcnt lgkmcnt(9)
	v_mul_f32_e32 v64, v64, v232
	v_mul_f32_e32 v65, v65, v233
	v_mul_f32_e32 v66, v66, v234
	v_mul_f32_e32 v67, v67, v235
	v_exp_f32_e32 v64, v64
	s_waitcnt lgkmcnt(8)
	v_mfma_f32_32x32x16_bf16 v[80:95], v[182:185], v[116:119], v[80:95]
	ds_read_b128 v[206:209], v216 offset:12544
	s_waitcnt lgkmcnt(8)
	v_mul_f32_e32 v68, v68, v236
	v_exp_f32_e32 v65, v65
	v_mul_f32_e32 v69, v69, v237
	v_exp_f32_e32 v66, v66
	v_mul_f32_e32 v70, v70, v238
	s_waitcnt lgkmcnt(7)
	v_mfma_f32_32x32x16_bf16 v[80:95], v[186:189], v[120:123], v[80:95]
	ds_read_b128 v[210:213], v217 offset:12544
	v_exp_f32_e32 v67, v67
	v_mul_f32_e32 v71, v71, v239
	v_add_u32_e32 v214, v214, v218
	v_add_u32_e32 v215, v215, v218
	v_add_u32_e32 v216, v216, v218
	v_add_u32_e32 v217, v217, v218
	s_waitcnt lgkmcnt(6)
	v_mfma_f32_32x32x16_bf16 v[80:95], v[190:193], v[124:127], v[80:95]
	ds_read_b128 v[182:185], v214 offset:49152
	v_exp_f32_e32 v68, v68
	v_cvt_pk_bf16_f32 v222, v64, v65
	v_exp_f32_e32 v69, v69
	v_cvt_pk_bf16_f32 v223, v66, v67
	v_exp_f32_e32 v70, v70
	s_waitcnt lgkmcnt(5)
	v_mfma_f32_32x32x16_bf16 v[80:95], v[194:197], v[128:131], v[80:95]
	ds_read_b128 v[186:189], v214 offset:53248
	v_exp_f32_e32 v71, v71
	v_cvt_pk_bf16_f32 v224, v68, v69
	v_cvt_pk_bf16_f32 v225, v70, v71
	v_mul_f32_e32 v72, v72, v240
	v_mul_f32_e32 v73, v73, v241
	s_waitcnt lgkmcnt(5)
	v_mfma_f32_32x32x16_bf16 v[80:95], v[198:201], v[132:135], v[80:95]
	ds_read_b128 v[190:193], v214 offset:57344
	v_mul_f32_e32 v74, v74, v242
	v_mul_f32_e32 v75, v75, v243
	v_exp_f32_e32 v72, v72
	v_mul_f32_e32 v76, v76, v244
	v_exp_f32_e32 v73, v73
	s_waitcnt lgkmcnt(5)
	v_mfma_f32_32x32x16_bf16 v[80:95], v[202:205], v[136:139], v[80:95]
	ds_read_b128 v[194:197], v214 offset:61440
	v_mul_f32_e32 v77, v77, v245
	v_exp_f32_e32 v74, v74
	v_mul_f32_e32 v78, v78, v246
	v_exp_f32_e32 v75, v75
	v_mul_f32_e32 v79, v79, v247
	s_waitcnt lgkmcnt(5)
; #define LAS __attribute__((address_space(3)))
; __device__ __forceinline__ f32x16 mfma32(bf16x8 a, bf16x8 b, f32x16 c) { return __builtin_amdgcn_mfma_f32_32x32x16_bf16(a, b, c, 0, 0, 0); }
; template <bool NOMAX>
; __device__ __forceinline__ void attn_block(const Params& P, LAS unsigned char* lds, int qR0, int h, int kR0, int kR1, int ntiles, int jmax, int nlast, int qvalid) {
;     ...
;             float ps = 0.f;
; #pragma unroll
;             for (int kt = 0; kt < 2; ++kt)
; #pragma unroll
;                 for (int e = 0; e < 16; ++e) { const float p = __builtin_amdgcn_exp2f(NOMAX ? sacc[kt][e] : sacc[kt][e] - mnew); sacc[kt][e] = p; ps += p; }
;             lrun += ps;
;             bf16x8 pf[2][2];
; #pragma unroll
;             for (int kt = 0; kt < 2; ++kt)
; #pragma unroll
;                 for (int s2 = 0; s2 < 2; ++s2) { u32x4 v; v.x = pk2(sacc[kt][8 * s2 + 0], sacc[kt][8 * s2 + 1]); v.y = pk2(sacc[kt][8 * s2 + 2], sacc[kt][8 * s2 + 3]); v.z = pk2(sacc[kt][8 * s2 + 4], sacc[kt][8 * s2 + 5]); v.w = pk2(sacc[kt][8 * s2 + 6], sacc[kt][8 * s2 + 7]); pf[kt][s2] = *(const bf16x8*)&v; }
; #pragma unroll
;             for (int dt = 0; dt < 4; ++dt)
; #pragma unroll
;                 for (int kt = 0; kt < 2; ++kt)
; #pragma unroll
;                     for (int s2 = 0; s2 < 2; ++s2) { const bf16x8 vf = *(const LAS bf16x8*)(vb + dt * (32 * 128) + oc[2 * kt + s2]);
;                         oacc[dt] = mfma32(vf, pf[kt][s2], oacc[dt]); }
	v_mfma_f32_32x32x16_bf16 v[80:95], v[206:209], v[140:143], v[80:95]
	ds_read_b128 v[198:201], v215 offset:49152
	v_exp_f32_e32 v76, v76
	v_cvt_pk_bf16_f32 v226, v72, v73
	v_exp_f32_e32 v77, v77
	v_cvt_pk_bf16_f32 v227, v74, v75
	ds_read_b128 v[232:235], v219 offset:128
	ds_read_b128 v[236:239], v219 offset:160
	s_waitcnt lgkmcnt(7)
	v_mfma_f32_32x32x16_bf16 v[80:95], v[210:213], v[144:147], v[80:95]
	ds_read_b128 v[202:205], v215 offset:53248
	v_exp_f32_e32 v78, v78
	v_exp_f32_e32 v79, v79
	v_cvt_pk_bf16_f32 v228, v76, v77
	v_cvt_pk_bf16_f32 v229, v78, v79
	ds_read_b128 v[240:243], v219 offset:192
	ds_read_b128 v[244:247], v219 offset:224
	s_waitcnt lgkmcnt(9)
	v_mfma_f32_32x32x16_bf16 v[48:63], v[182:185], v[222:225], v[48:63]
	ds_read_b128 v[206:209], v215 offset:57344
	v_add_f32_e32 v231, v64, v65
	v_add_f32_e32 v231, v66, v231
	v_add_f32_e32 v231, v67, v231
	v_add_f32_e32 v231, v68, v231
	s_waitcnt lgkmcnt(9)
	v_mfma_f32_32x32x16_bf16 v[32:47], v[186:189], v[222:225], v[32:47]
	ds_read_b128 v[210:213], v215 offset:61440
	v_add_f32_e32 v231, v69, v231
	v_add_f32_e32 v231, v70, v231
	v_add_f32_e32 v231, v71, v231
	v_add_f32_e32 v231, v72, v231
	s_waitcnt lgkmcnt(9)
	v_mfma_f32_32x32x16_bf16 v[16:31], v[190:193], v[222:225], v[16:31]
	ds_read_b128 v[182:185], v216 offset:49152
	v_add_f32_e32 v231, v73, v231
	v_add_f32_e32 v231, v74, v231
	v_add_f32_e32 v231, v75, v231
	v_add_f32_e32 v231, v76, v231
	s_waitcnt lgkmcnt(9)
	v_mfma_f32_32x32x16_bf16 v[0:15], v[194:197], v[222:225], v[0:15]
	ds_read_b128 v[186:189], v216 offset:53248
	s_waitcnt lgkmcnt(8)
	v_mul_f32_e32 v80, v80, v232
	v_mul_f32_e32 v81, v81, v233
	v_mul_f32_e32 v82, v82, v234
	v_mul_f32_e32 v83, v83, v235
	v_mfma_f32_32x32x16_bf16 v[48:63], v[198:201], v[226:229], v[48:63]
	ds_read_b128 v[190:193], v216 offset:57344
	v_exp_f32_e32 v80, v80
	s_waitcnt lgkmcnt(8)
	v_mul_f32_e32 v84, v84, v236
	v_exp_f32_e32 v81, v81
	v_mul_f32_e32 v85, v85, v237
	s_waitcnt lgkmcnt(7)
	v_mfma_f32_32x32x16_bf16 v[32:47], v[202:205], v[226:229], v[32:47]
	ds_read_b128 v[194:197], v216 offset:61440
	v_exp_f32_e32 v82, v82
	v_mul_f32_e32 v86, v86, v238
	v_exp_f32_e32 v83, v83
	v_mul_f32_e32 v87, v87, v239
	s_waitcnt lgkmcnt(5)
	v_mfma_f32_32x32x16_bf16 v[16:31], v[206:209], v[226:229], v[16:31]
	ds_read_b128 v[198:201], v217 offset:49152
	v_exp_f32_e32 v84, v84
	v_cvt_pk_bf16_f32 v248, v80, v81
	v_exp_f32_e32 v85, v85
	v_cvt_pk_bf16_f32 v249, v82, v83
	s_waitcnt lgkmcnt(5)
	v_mfma_f32_32x32x16_bf16 v[0:15], v[210:213], v[226:229], v[0:15]
	ds_read_b128 v[202:205], v217 offset:53248
	v_exp_f32_e32 v86, v86
	v_exp_f32_e32 v87, v87
	v_cvt_pk_bf16_f32 v250, v84, v85
	v_cvt_pk_bf16_f32 v251, v86, v87
	v_add_f32_e32 v231, v77, v231
	v_add_f32_e32 v231, v78, v231
	v_add_f32_e32 v231, v79, v231
	s_waitcnt lgkmcnt(5)
	v_mfma_f32_32x32x16_bf16 v[48:63], v[182:185], v[248:251], v[48:63]
	ds_read_b128 v[206:209], v217 offset:57344
	v_mul_f32_e32 v88, v88, v240
	v_mul_f32_e32 v89, v89, v241
	v_mul_f32_e32 v90, v90, v242
	v_mul_f32_e32 v91, v91, v243
	v_exp_f32_e32 v88, v88
	s_waitcnt lgkmcnt(5)
	v_mfma_f32_32x32x16_bf16 v[32:47], v[186:189], v[248:251], v[32:47]
	ds_read_b128 v[210:213], v217 offset:61440
	v_mul_f32_e32 v92, v92, v244
	v_exp_f32_e32 v89, v89
	v_mul_f32_e32 v93, v93, v245
	v_exp_f32_e32 v90, v90
	v_mul_f32_e32 v94, v94, v246
	s_waitcnt lgkmcnt(5)
	v_mfma_f32_32x32x16_bf16 v[16:31], v[190:193], v[248:251], v[16:31]
	v_exp_f32_e32 v91, v91
	v_mul_f32_e32 v95, v95, v247
	v_exp_f32_e32 v92, v92
	v_cvt_pk_bf16_f32 v64, v88, v89
	v_exp_f32_e32 v93, v93
	s_waitcnt lgkmcnt(4)
	v_mfma_f32_32x32x16_bf16 v[0:15], v[194:197], v[248:251], v[0:15]
	v_cvt_pk_bf16_f32 v65, v90, v91
	v_exp_f32_e32 v94, v94
	v_exp_f32_e32 v95, v95
	v_cvt_pk_bf16_f32 v66, v92, v93
	v_cvt_pk_bf16_f32 v67, v94, v95
	v_add_f32_e32 v252, v80, v81
	v_add_f32_e32 v252, v82, v252
	s_waitcnt lgkmcnt(3)
	v_mfma_f32_32x32x16_bf16 v[48:63], v[198:201], v[64:67], v[48:63]
	v_add_f32_e32 v252, v83, v252
	v_add_f32_e32 v252, v84, v252
	v_add_f32_e32 v252, v85, v252
	v_add_f32_e32 v252, v86, v252
	s_waitcnt lgkmcnt(2)
	v_mfma_f32_32x32x16_bf16 v[32:47], v[202:205], v[64:67], v[32:47]
	v_add_f32_e32 v252, v87, v252
	v_add_f32_e32 v252, v88, v252
	v_add_f32_e32 v252, v89, v252
	v_add_f32_e32 v252, v90, v252
	s_waitcnt lgkmcnt(1)
	v_mfma_f32_32x32x16_bf16 v[16:31], v[206:209], v[64:67], v[16:31]
	v_add_f32_e32 v252, v91, v252
	v_add_f32_e32 v252, v92, v252
	v_add_f32_e32 v252, v93, v252
	v_add_f32_e32 v252, v94, v252
	s_waitcnt lgkmcnt(0)
	v_mfma_f32_32x32x16_bf16 v[0:15], v[210:213], v[64:67], v[0:15]
	v_add_f32_e32 v252, v95, v252
	v_add_f32_e32 v231, v231, v252
	v_add_f32_e32 v164, v164, v231
	s_branch .Lattn_tail_a
; #define LAS __attribute__((address_space(3)))
; __device__ __forceinline__ f32x16 mfma32(bf16x8 a, bf16x8 b, f32x16 c) { return __builtin_amdgcn_mfma_f32_32x32x16_bf16(a, b, c, 0, 0, 0); }
; __device__ __forceinline__ void attn_stage_issue(const Params& P, LAS unsigned char* lds, const AttnStage& st, int R0, int buf, int tid) {
;     const char* ws = (const char*)P.ws; const int w = __builtin_amdgcn_readfirstlane(tid >> 6);
; #pragma unroll
;     for (int i = 0; i < 3; ++i) __builtin_amdgcn_global_load_lds((const unsigned*)(ws + (st.kofs[i] + (unsigned)R0 * st.kstr[i])), (LAS unsigned*)(lds + L_K0 + buf * KBUF + (w * 3 + i) * 1024), 16, 0, 0);
; #pragma unroll
;     for (int i = 0; i < 2; ++i) __builtin_amdgcn_global_load_lds((const unsigned*)(ws + (st.vofs[i] + (unsigned)R0 * 2u)), (LAS unsigned*)(lds + L_V0 + buf * VBUF + (w * 2 + i) * 1024), 16, 0, 0);
; }
; template <bool NOMAX>
; __device__ __forceinline__ void attn_block(const Params& P, LAS unsigned char* lds, int qR0, int h, int kR0, int kR1, int ntiles, int jmax, int nlast, int qvalid) {
;     ...
;             const LAS unsigned char* kb = lds + L_K0 + buf * KBUF + r * 384; const LAS unsigned char* vb = lds + L_V0 + buf * VBUF + r * 128;
;             const LAS unsigned char* rkb = lds + L_RKT + j * 256 + 16 * hh;
;             f32x16 sacc[2];
; #pragma unroll
;             for (int kt = 0; kt < 2; ++kt) {
; #pragma unroll
;                 for (int e = 0; e < 16; ++e) sacc[kt][e] = 0.f;
; #pragma unroll
;                 for (int s = 0; s < 12; ++s) { const bf16x8 kf = *(const LAS bf16x8*)(kb + kt * (32 * 384) + (s >> 2) * 128 + oc[s & 3]); sacc[kt] = mfma32(kf, qf[s], sacc[kt]); }
;             }
; #pragma unroll
;             for (int kt = 0; kt < 2; ++kt)
; #pragma unroll
;                 for (int gq = 0; gq < 4; ++gq) { const f32x4 rk4 = *(const LAS f32x4*)(rkb + (32 * kt + 8 * gq) * 4);
; #pragma unroll
;                     for (int i = 0; i < 4; ++i) sacc[kt][4 * gq + i] *= rk4[i]; }
.Lattn_late_a:
	v_lshl_add_u32 v254, v181, v173, v170
	s_mov_b32 m0, s59
	s_nop 0
	global_load_lds_dwordx4 v254, s[18:19]
	v_lshl_add_u32 v254, v181, v174, v171
	s_add_i32 m0, s59, 0x400
	s_nop 0
	global_load_lds_dwordx4 v254, s[18:19]
	v_lshl_add_u32 v254, v181, v175, v172
	s_add_i32 m0, s59, 0x800
	s_nop 0
	global_load_lds_dwordx4 v254, s[18:19]
	s_mov_b32 m0, s60
	s_nop 0
	global_load_lds_dwordx4 v180, s[18:19]
	s_add_i32 m0, s60, 0x400
	s_nop 0
	global_load_lds_dwordx4 v179, s[18:19]
	s_mul_i32 s58, s57, 0x6000
	v_add_u32_e32 v253, s58, v177
	v_add_u32_e32 v214, v253, v168
	v_add_u32_e32 v215, v253, v167
	v_add_u32_e32 v216, v253, v166
	v_add_u32_e32 v217, v253, v165
	ds_read_b128 v[182:185], v214
	ds_read_b128 v[186:189], v215
	ds_read_b128 v[190:193], v216
	ds_read_b128 v[194:197], v217
	ds_read_b128 v[198:201], v214 offset:128
	ds_read_b128 v[202:205], v215 offset:128
	s_waitcnt lgkmcnt(5)
	v_mfma_f32_32x32x16_bf16 v[64:79], v[182:185], v[100:103], 0
	ds_read_b128 v[206:209], v216 offset:128
	v_add_u32_e32 v219, s56, v178
	s_waitcnt lgkmcnt(5)
	v_mfma_f32_32x32x16_bf16 v[64:79], v[186:189], v[104:107], v[64:79]
	ds_read_b128 v[210:213], v217 offset:128
	v_add_u32_e32 v219, 0x14300, v219
	s_waitcnt lgkmcnt(5)
	v_mfma_f32_32x32x16_bf16 v[64:79], v[190:193], v[108:111], v[64:79]
	ds_read_b128 v[182:185], v214 offset:256
	v_lshl_add_u32 v218, s57, 14, v176
	s_waitcnt lgkmcnt(5)
	v_mfma_f32_32x32x16_bf16 v[64:79], v[194:197], v[112:115], v[64:79]
	ds_read_b128 v[186:189], v215 offset:256
	v_sub_u32_e32 v218, v218, v253
	s_waitcnt lgkmcnt(5)
	v_mfma_f32_32x32x16_bf16 v[64:79], v[198:201], v[116:119], v[64:79]
	ds_read_b128 v[190:193], v216 offset:256
	s_waitcnt lgkmcnt(5)
	v_mfma_f32_32x32x16_bf16 v[64:79], v[202:205], v[120:123], v[64:79]
	ds_read_b128 v[194:197], v217 offset:256
	s_waitcnt lgkmcnt(5)
	v_mfma_f32_32x32x16_bf16 v[64:79], v[206:209], v[124:127], v[64:79]
	ds_read_b128 v[198:201], v214 offset:12288
	s_waitcnt lgkmcnt(5)
	v_mfma_f32_32x32x16_bf16 v[64:79], v[210:213], v[128:131], v[64:79]
	ds_read_b128 v[202:205], v215 offset:12288
	s_waitcnt lgkmcnt(5)
	v_mfma_f32_32x32x16_bf16 v[64:79], v[182:185], v[132:135], v[64:79]
	ds_read_b128 v[206:209], v216 offset:12288
	s_waitcnt lgkmcnt(5)
	v_mfma_f32_32x32x16_bf16 v[64:79], v[186:189], v[136:139], v[64:79]
	ds_read_b128 v[210:213], v217 offset:12288
	ds_read_b128 v[232:235], v219
	s_waitcnt lgkmcnt(6)
	v_mfma_f32_32x32x16_bf16 v[64:79], v[190:193], v[140:143], v[64:79]
	ds_read_b128 v[182:185], v214 offset:12416
	ds_read_b128 v[236:239], v219 offset:32
	s_waitcnt lgkmcnt(7)
	v_mfma_f32_32x32x16_bf16 v[64:79], v[194:197], v[144:147], v[64:79]
	ds_read_b128 v[186:189], v215 offset:12416
	ds_read_b128 v[240:243], v219 offset:64
	s_waitcnt lgkmcnt(8)
	v_mfma_f32_32x32x16_bf16 v[80:95], v[198:201], v[100:103], 0
	ds_read_b128 v[190:193], v216 offset:12416
	ds_read_b128 v[244:247], v219 offset:96
	s_waitcnt lgkmcnt(9)
	v_mfma_f32_32x32x16_bf16 v[80:95], v[202:205], v[104:107], v[80:95]
	ds_read_b128 v[194:197], v217 offset:12416
	s_waitcnt lgkmcnt(9)
	v_mfma_f32_32x32x16_bf16 v[80:95], v[206:209], v[108:111], v[80:95]
	ds_read_b128 v[198:201], v214 offset:12544
	s_waitcnt lgkmcnt(9)
	v_mfma_f32_32x32x16_bf16 v[80:95], v[210:213], v[112:115], v[80:95]
	ds_read_b128 v[202:205], v215 offset:12544
	s_waitcnt lgkmcnt(9)
	v_mul_f32_e32 v64, v64, v232
	v_mul_f32_e32 v65, v65, v233
	v_mul_f32_e32 v66, v66, v234
	v_mul_f32_e32 v67, v67, v235
	v_exp_f32_e32 v64, v64
	s_waitcnt lgkmcnt(8)
	v_mfma_f32_32x32x16_bf16 v[80:95], v[182:185], v[116:119], v[80:95]
	ds_read_b128 v[206:209], v216 offset:12544
	s_waitcnt lgkmcnt(8)
	v_mul_f32_e32 v68, v68, v236
	v_exp_f32_e32 v65, v65
	v_mul_f32_e32 v69, v69, v237
	v_exp_f32_e32 v66, v66
	v_mul_f32_e32 v70, v70, v238
	s_waitcnt lgkmcnt(7)
	v_mfma_f32_32x32x16_bf16 v[80:95], v[186:189], v[120:123], v[80:95]
	ds_read_b128 v[210:213], v217 offset:12544
	v_exp_f32_e32 v67, v67
	v_mul_f32_e32 v71, v71, v239
	v_add_u32_e32 v214, v214, v218
	v_add_u32_e32 v215, v215, v218
	v_add_u32_e32 v216, v216, v218
	v_add_u32_e32 v217, v217, v218
	s_waitcnt lgkmcnt(6)
	v_mfma_f32_32x32x16_bf16 v[80:95], v[190:193], v[124:127], v[80:95]
	ds_read_b128 v[182:185], v214 offset:49152
	v_exp_f32_e32 v68, v68
	v_cvt_pk_bf16_f32 v222, v64, v65
	v_exp_f32_e32 v69, v69
	v_cvt_pk_bf16_f32 v223, v66, v67
	v_exp_f32_e32 v70, v70
	s_waitcnt lgkmcnt(5)
	v_mfma_f32_32x32x16_bf16 v[80:95], v[194:197], v[128:131], v[80:95]
	ds_read_b128 v[186:189], v214 offset:53248
	v_exp_f32_e32 v71, v71
	v_cvt_pk_bf16_f32 v224, v68, v69
	v_cvt_pk_bf16_f32 v225, v70, v71
	v_mul_f32_e32 v72, v72, v240
	v_mul_f32_e32 v73, v73, v241
	s_waitcnt lgkmcnt(5)
	v_mfma_f32_32x32x16_bf16 v[80:95], v[198:201], v[132:135], v[80:95]
	ds_read_b128 v[190:193], v214 offset:57344
	v_mul_f32_e32 v74, v74, v242
	v_mul_f32_e32 v75, v75, v243
	v_exp_f32_e32 v72, v72
	v_mul_f32_e32 v76, v76, v244
	v_exp_f32_e32 v73, v73
	s_waitcnt lgkmcnt(5)
; #define LAS __attribute__((address_space(3)))
; __device__ __forceinline__ f32x16 mfma32(bf16x8 a, bf16x8 b, f32x16 c) { return __builtin_amdgcn_mfma_f32_32x32x16_bf16(a, b, c, 0, 0, 0); }
; template <bool NOMAX>
; __device__ __forceinline__ void attn_block(const Params& P, LAS unsigned char* lds, int qR0, int h, int kR0, int kR1, int ntiles, int jmax, int nlast, int qvalid) {
;     ...
;             float ps = 0.f;
; #pragma unroll
;             for (int kt = 0; kt < 2; ++kt)
; #pragma unroll
;                 for (int e = 0; e < 16; ++e) { const float p = __builtin_amdgcn_exp2f(NOMAX ? sacc[kt][e] : sacc[kt][e] - mnew); sacc[kt][e] = p; ps += p; }
;             lrun += ps;
;             bf16x8 pf[2][2];
; #pragma unroll
;             for (int kt = 0; kt < 2; ++kt)
; #pragma unroll
;                 for (int s2 = 0; s2 < 2; ++s2) { u32x4 v; v.x = pk2(sacc[kt][8 * s2 + 0], sacc[kt][8 * s2 + 1]); v.y = pk2(sacc[kt][8 * s2 + 2], sacc[kt][8 * s2 + 3]); v.z = pk2(sacc[kt][8 * s2 + 4], sacc[kt][8 * s2 + 5]); v.w = pk2(sacc[kt][8 * s2 + 6], sacc[kt][8 * s2 + 7]); pf[kt][s2] = *(const bf16x8*)&v; }
; #pragma unroll
;             for (int dt = 0; dt < 4; ++dt)
; #pragma unroll
;                 for (int kt = 0; kt < 2; ++kt)
; #pragma unroll
;                     for (int s2 = 0; s2 < 2; ++s2) { const bf16x8 vf = *(const LAS bf16x8*)(vb + dt * (32 * 128) + oc[2 * kt + s2]);
;                         oacc[dt] = mfma32(vf, pf[kt][s2], oacc[dt]); }
	v_mfma_f32_32x32x16_bf16 v[80:95], v[202:205], v[136:139], v[80:95]
	ds_read_b128 v[194:197], v214 offset:61440
	v_mul_f32_e32 v77, v77, v245
	v_exp_f32_e32 v74, v74
	v_mul_f32_e32 v78, v78, v246
	v_exp_f32_e32 v75, v75
	v_mul_f32_e32 v79, v79, v247
	s_waitcnt lgkmcnt(5)
	v_mfma_f32_32x32x16_bf16 v[80:95], v[206:209], v[140:143], v[80:95]
	ds_read_b128 v[198:201], v215 offset:49152
	v_exp_f32_e32 v76, v76
	v_cvt_pk_bf16_f32 v226, v72, v73
	v_exp_f32_e32 v77, v77
	v_cvt_pk_bf16_f32 v227, v74, v75
	ds_read_b128 v[232:235], v219 offset:128
	ds_read_b128 v[236:239], v219 offset:160
	s_waitcnt lgkmcnt(7)
	v_mfma_f32_32x32x16_bf16 v[80:95], v[210:213], v[144:147], v[80:95]
	ds_read_b128 v[202:205], v215 offset:53248
	v_exp_f32_e32 v78, v78
	v_exp_f32_e32 v79, v79
	v_cvt_pk_bf16_f32 v228, v76, v77
	v_cvt_pk_bf16_f32 v229, v78, v79
	ds_read_b128 v[240:243], v219 offset:192
	ds_read_b128 v[244:247], v219 offset:224
	s_waitcnt lgkmcnt(9)
	v_mfma_f32_32x32x16_bf16 v[48:63], v[182:185], v[222:225], v[48:63]
	ds_read_b128 v[206:209], v215 offset:57344
	v_add_f32_e32 v231, v64, v65
	v_add_f32_e32 v231, v66, v231
	v_add_f32_e32 v231, v67, v231
	v_add_f32_e32 v231, v68, v231
	s_waitcnt lgkmcnt(9)
	v_mfma_f32_32x32x16_bf16 v[32:47], v[186:189], v[222:225], v[32:47]
	ds_read_b128 v[210:213], v215 offset:61440
	v_add_f32_e32 v231, v69, v231
	v_add_f32_e32 v231, v70, v231
	v_add_f32_e32 v231, v71, v231
	v_add_f32_e32 v231, v72, v231
	s_waitcnt lgkmcnt(9)
	v_mfma_f32_32x32x16_bf16 v[16:31], v[190:193], v[222:225], v[16:31]
	ds_read_b128 v[182:185], v216 offset:49152
	v_add_f32_e32 v231, v73, v231
	v_add_f32_e32 v231, v74, v231
	v_add_f32_e32 v231, v75, v231
	v_add_f32_e32 v231, v76, v231
	s_waitcnt lgkmcnt(9)
	v_mfma_f32_32x32x16_bf16 v[0:15], v[194:197], v[222:225], v[0:15]
	ds_read_b128 v[186:189], v216 offset:53248
	s_waitcnt lgkmcnt(8)
	v_mul_f32_e32 v80, v80, v232
	v_mul_f32_e32 v81, v81, v233
	v_mul_f32_e32 v82, v82, v234
	v_mul_f32_e32 v83, v83, v235
	v_mfma_f32_32x32x16_bf16 v[48:63], v[198:201], v[226:229], v[48:63]
	ds_read_b128 v[190:193], v216 offset:57344
	v_exp_f32_e32 v80, v80
	s_waitcnt lgkmcnt(8)
	v_mul_f32_e32 v84, v84, v236
	v_exp_f32_e32 v81, v81
	v_mul_f32_e32 v85, v85, v237
	s_waitcnt lgkmcnt(7)
	v_mfma_f32_32x32x16_bf16 v[32:47], v[202:205], v[226:229], v[32:47]
	ds_read_b128 v[194:197], v216 offset:61440
	v_exp_f32_e32 v82, v82
	v_mul_f32_e32 v86, v86, v238
	v_exp_f32_e32 v83, v83
	v_mul_f32_e32 v87, v87, v239
	s_waitcnt lgkmcnt(5)
	v_mfma_f32_32x32x16_bf16 v[16:31], v[206:209], v[226:229], v[16:31]
	ds_read_b128 v[198:201], v217 offset:49152
	v_exp_f32_e32 v84, v84
	v_cvt_pk_bf16_f32 v248, v80, v81
	v_exp_f32_e32 v85, v85
	v_cvt_pk_bf16_f32 v249, v82, v83
	s_waitcnt lgkmcnt(5)
	v_mfma_f32_32x32x16_bf16 v[0:15], v[210:213], v[226:229], v[0:15]
	ds_read_b128 v[202:205], v217 offset:53248
	v_exp_f32_e32 v86, v86
	v_exp_f32_e32 v87, v87
	v_cvt_pk_bf16_f32 v250, v84, v85
	v_cvt_pk_bf16_f32 v251, v86, v87
	v_add_f32_e32 v231, v77, v231
	v_add_f32_e32 v231, v78, v231
	v_add_f32_e32 v231, v79, v231
	s_waitcnt lgkmcnt(5)
	v_mfma_f32_32x32x16_bf16 v[48:63], v[182:185], v[248:251], v[48:63]
	ds_read_b128 v[206:209], v217 offset:57344
	v_mul_f32_e32 v88, v88, v240
	v_mul_f32_e32 v89, v89, v241
	v_mul_f32_e32 v90, v90, v242
	v_mul_f32_e32 v91, v91, v243
	v_exp_f32_e32 v88, v88
	s_waitcnt lgkmcnt(5)
	v_mfma_f32_32x32x16_bf16 v[32:47], v[186:189], v[248:251], v[32:47]
	ds_read_b128 v[210:213], v217 offset:61440
	v_mul_f32_e32 v92, v92, v244
	v_exp_f32_e32 v89, v89
	v_mul_f32_e32 v93, v93, v245
	v_exp_f32_e32 v90, v90
	v_mul_f32_e32 v94, v94, v246
	s_waitcnt lgkmcnt(5)
	v_mfma_f32_32x32x16_bf16 v[16:31], v[190:193], v[248:251], v[16:31]
	v_exp_f32_e32 v91, v91
	v_mul_f32_e32 v95, v95, v247
	v_exp_f32_e32 v92, v92
	v_cvt_pk_bf16_f32 v64, v88, v89
	v_exp_f32_e32 v93, v93
	s_waitcnt lgkmcnt(4)
	v_mfma_f32_32x32x16_bf16 v[0:15], v[194:197], v[248:251], v[0:15]
	v_cvt_pk_bf16_f32 v65, v90, v91
	v_exp_f32_e32 v94, v94
	v_exp_f32_e32 v95, v95
	v_cvt_pk_bf16_f32 v66, v92, v93
	v_cvt_pk_bf16_f32 v67, v94, v95
	v_add_f32_e32 v252, v80, v81
	v_add_f32_e32 v252, v82, v252
	s_waitcnt lgkmcnt(3)
	v_mfma_f32_32x32x16_bf16 v[48:63], v[198:201], v[64:67], v[48:63]
	v_add_f32_e32 v252, v83, v252
	v_add_f32_e32 v252, v84, v252
	v_add_f32_e32 v252, v85, v252
	v_add_f32_e32 v252, v86, v252
	s_waitcnt lgkmcnt(2)
	v_mfma_f32_32x32x16_bf16 v[32:47], v[202:205], v[64:67], v[32:47]
	v_add_f32_e32 v252, v87, v252
	v_add_f32_e32 v252, v88, v252
	v_add_f32_e32 v252, v89, v252
	v_add_f32_e32 v252, v90, v252
	s_waitcnt lgkmcnt(1)
	v_mfma_f32_32x32x16_bf16 v[16:31], v[206:209], v[64:67], v[16:31]
	v_add_f32_e32 v252, v91, v252
	v_add_f32_e32 v252, v92, v252
	v_add_f32_e32 v252, v93, v252
	v_add_f32_e32 v252, v94, v252
	s_waitcnt lgkmcnt(0)
	v_mfma_f32_32x32x16_bf16 v[0:15], v[210:213], v[64:67], v[0:15]
	v_add_f32_e32 v252, v95, v252
	v_add_f32_e32 v231, v231, v252
	v_add_f32_e32 v164, v164, v231
	s_branch .Lattn_tail_a
